# grid barrier poll loop sleeps 256 instead of 64 cycles between polls (less pressure on the polled line while the arrival atomics land)
# speedup vs baseline: 1.0107x; 1.0107x over previous
.Lxb2_poll:
	global_load_dword v2, v131, s[4:5] sc1
	s_add_i32 s7, s7, 1
	s_waitcnt vmcnt(0)
	v_cmp_lt_u32_e32 vcc, v2, v6
	s_nop 1
	s_cbranch_vccz .Lxb2_done
	s_sleep 4
	s_cmp_lt_u32 s7, 0x40001
	s_cbranch_scc1 .Lxb2_poll
